# phase_h0 H stores sc1 write-through (shorter writeback at the barrier before in-proj), on the sc1 nt version
# speedup vs baseline: 1.0005x; 1.0005x over previous
; DI void phase_h0(const P& p) {
;     ...
; #pragma unroll
;       for (int i = 0; i < 4; ++i) {
;         const float4 v = half ? vb[i] : va[i];
;         uint2 o;
;         o.x = pack2(v.x * (1.f + sc[i].x) + sh[i].x, v.y * (1.f + sc[i].y) + sh[i].y);
;         o.y = pack2(v.z * (1.f + sc[i].z) + sh[i].z, v.w * (1.f + sc[i].w) + sh[i].w);
;         *(uint2*)(p.H + (size_t)rr * 1024 + i * 256 + lane * 4) = o;
;       }
.LBB0_14:
	s_or_b64 exec, exec, s[40:41]
	s_waitcnt vmcnt(3)
	v_pk_fma_f32 v[46:47], v[46:47], v[74:75], v[6:7]
	v_pk_fma_f32 v[48:49], v[48:49], v[76:77], v[8:9]
	s_waitcnt vmcnt(2)
	v_pk_fma_f32 v[42:43], v[42:43], v[62:63], v[14:15]
	v_pk_fma_f32 v[44:45], v[44:45], v[58:59], v[16:17]
	s_waitcnt vmcnt(1)
	v_pk_fma_f32 v[38:39], v[38:39], v[60:61], v[22:23]
	v_pk_fma_f32 v[40:41], v[40:41], v[54:55], v[24:25]
	s_waitcnt vmcnt(0)
	v_pk_fma_f32 v[34:35], v[34:35], v[56:57], v[30:31]
	v_pk_fma_f32 v[36:37], v[36:37], v[50:51], v[32:33]
	v_cvt_pk_bf16_f32 v46, v46, v47
	v_cvt_pk_bf16_f32 v47, v48, v49
	v_lshl_add_u64 v[48:49], v[70:71], 0, v[68:69]
	v_cvt_pk_bf16_f32 v42, v42, v43
	v_cvt_pk_bf16_f32 v43, v44, v45
	v_cvt_pk_bf16_f32 v38, v38, v39
	v_cvt_pk_bf16_f32 v39, v40, v41
	v_cvt_pk_bf16_f32 v34, v34, v35
	v_cvt_pk_bf16_f32 v35, v36, v37
	global_store_dwordx2 v[48:49], v[46:47], off sc1
	global_store_dwordx2 v[48:49], v[42:43], off offset:512 sc1
	global_store_dwordx2 v[48:49], v[38:39], off offset:1024 sc1
	global_store_dwordx2 v[48:49], v[34:35], off offset:1536 sc1

; DI void phase_h0(const P& p) {
;     ...
;     for (int half = 0; half < 2; ++half) {
;       const int rr = half ? rowb : row;
;       if (half && !two) break;
;       const int mr = rr < MLAT ? (rr >> 11) : 16;
;       if (mr != cur_mr) {
;         cur_mr = mr;
;         const float* md = p.mod + (size_t)mr * 3072;
; #pragma unroll
;         for (int i = 0; i < 4; ++i) {
;           sh[i] = *(const float4*)(md + i * 256 + lane * 4);
;           sc[i] = *(const float4*)(md + 1024 + i * 256 + lane * 4);
;         }
;       }
; #pragma unroll
;       for (int i = 0; i < 4; ++i) {
;         const float4 v = half ? vb[i] : va[i];
;         uint2 o;
;         o.x = pack2(v.x * (1.f + sc[i].x) + sh[i].x, v.y * (1.f + sc[i].y) + sh[i].y);
;         o.y = pack2(v.z * (1.f + sc[i].z) + sh[i].z, v.w * (1.f + sc[i].w) + sh[i].w);
;         *(uint2*)(p.H + (size_t)rr * 1024 + i * 256 + lane * 4) = o;
;       }
.LBB0_18:
	s_or_b64 exec, exec, s[46:47]
	s_waitcnt vmcnt(1)
	v_pk_add_f32 v[74:75], v[18:19], 1.0 op_sel_hi:[1,0]
	v_pk_add_f32 v[76:77], v[20:21], 1.0 op_sel_hi:[1,0]
	v_pk_fma_f32 v[62:63], v[62:63], v[74:75], v[6:7]
	v_pk_fma_f32 v[64:65], v[64:65], v[76:77], v[8:9]
	v_cvt_pk_bf16_f32 v62, v62, v63
	v_cvt_pk_bf16_f32 v63, v64, v65
	v_lshl_add_u64 v[64:65], v[72:73], 0, v[68:69]
	global_store_dwordx2 v[64:65], v[62:63], off sc1
	v_pk_add_f32 v[62:63], v[2:3], 1.0 op_sel_hi:[1,0]
	s_nop 0
	v_pk_fma_f32 v[58:59], v[58:59], v[62:63], v[14:15]
	s_nop 0
	v_cvt_pk_bf16_f32 v82, v58, v59
	v_pk_add_f32 v[58:59], v[4:5], 1.0 op_sel_hi:[1,0]
	s_nop 0
	v_pk_fma_f32 v[60:61], v[60:61], v[58:59], v[16:17]
	s_nop 0
	v_cvt_pk_bf16_f32 v83, v60, v61
	v_pk_add_f32 v[60:61], v[10:11], 1.0 op_sel_hi:[1,0]
	global_store_dwordx2 v[64:65], v[82:83], off offset:512 sc1
	v_pk_fma_f32 v[54:55], v[54:55], v[60:61], v[22:23]
	s_nop 0
	v_cvt_pk_bf16_f32 v82, v54, v55
	v_pk_add_f32 v[54:55], v[12:13], 1.0 op_sel_hi:[1,0]
	s_nop 0
	v_pk_fma_f32 v[56:57], v[56:57], v[54:55], v[24:25]
	s_nop 0
	v_cvt_pk_bf16_f32 v83, v56, v57
	s_waitcnt vmcnt(2)
	v_pk_add_f32 v[56:57], v[26:27], 1.0 op_sel_hi:[1,0]
	global_store_dwordx2 v[64:65], v[82:83], off offset:1024 sc1
	v_pk_fma_f32 v[50:51], v[50:51], v[56:57], v[30:31]
	s_nop 0
	v_cvt_pk_bf16_f32 v82, v50, v51
	v_pk_add_f32 v[50:51], v[28:29], 1.0 op_sel_hi:[1,0]
	s_nop 0
	v_pk_fma_f32 v[52:53], v[52:53], v[50:51], v[32:33]
	s_nop 0
	v_cvt_pk_bf16_f32 v83, v52, v53
	global_store_dwordx2 v[64:65], v[82:83], off offset:1536 sc1
	s_and_saveexec_b64 s[46:47], s[40:41]
	s_cbranch_execz .LBB0_15
	v_min_i32_e32 v52, 0x8000, v80
	v_ashrrev_i32_e32 v52, 11, v52
	v_cmp_ne_u32_e32 vcc, v52, v79
	s_and_saveexec_b64 s[40:41], vcc
	s_cbranch_execz .LBB0_14
	v_readlane_b32 s52, v255, 28
	v_mul_hi_i32_i24_e32 v3, 0x3000, v52
	v_mul_i32_i24_e32 v2, 0x3000, v52
	v_readlane_b32 s54, v255, 30
	v_readlane_b32 s55, v255, 31
	v_mov_b32_e32 v79, v52
	v_readlane_b32 s53, v255, 29
	v_lshl_add_u64 v[2:3], s[54:55], 0, v[2:3]
	v_lshl_add_u64 v[30:31], v[2:3], 0, v[0:1]
	v_lshl_add_u64 v[6:7], v[30:31], 0, s[90:91]
	global_load_dwordx4 v[2:5], v[6:7], off offset:1024
	global_load_dwordx4 v[10:13], v[6:7], off offset:2048
	v_add_co_u32_e32 v8, vcc, 0x1000, v30
	v_readlane_b32 s56, v255, 32
	s_nop 0
	v_addc_co_u32_e32 v9, vcc, 0, v31, vcc
	global_load_dwordx4 v[26:29], v[6:7], off offset:3072
	global_load_dwordx4 v[18:21], v[8:9], off
	s_nop 0
	global_load_dwordx4 v[6:9], v[30:31], off
	global_load_dwordx4 v[14:17], v[30:31], off offset:1024
	global_load_dwordx4 v[22:25], v[30:31], off offset:2048
	s_nop 0
	global_load_dwordx4 v[30:33], v[30:31], off offset:3072
	v_readlane_b32 s57, v255, 33
	v_readlane_b32 s58, v255, 34
	v_readlane_b32 s59, v255, 35
	s_waitcnt vmcnt(7)
	v_pk_add_f32 v[62:63], v[2:3], 1.0 op_sel_hi:[1,0]
	v_pk_add_f32 v[58:59], v[4:5], 1.0 op_sel_hi:[1,0]
	s_waitcnt vmcnt(6)
	v_pk_add_f32 v[60:61], v[10:11], 1.0 op_sel_hi:[1,0]
	v_pk_add_f32 v[54:55], v[12:13], 1.0 op_sel_hi:[1,0]
	s_waitcnt vmcnt(5)
	v_pk_add_f32 v[56:57], v[26:27], 1.0 op_sel_hi:[1,0]
	v_pk_add_f32 v[50:51], v[28:29], 1.0 op_sel_hi:[1,0]
	s_waitcnt vmcnt(4)
	v_pk_add_f32 v[74:75], v[18:19], 1.0 op_sel_hi:[1,0]
	v_pk_add_f32 v[76:77], v[20:21], 1.0 op_sel_hi:[1,0]
	s_branch .LBB0_14
